# GLA scan: next-chunk q/k/low-rank prefetch issued at the head of section C (raw q/k copied out of the prefetch registers first); V-DMA wait at the end of C counts the younger stores/loads
# baseline (speedup 1.0000x reference)
.Lscan_nofl2:
	s_mov_b32 s99, -1
	s_cmp_eq_u32 s50, 3
	s_cbranch_scc1 .Lscan_pfc_none
	s_add_i32 s99, s5, 1
	s_bitcmp1_b32 s8, 0
	s_cbranch_scc0 .Lscan_pfc_have
	s_sub_i32 s99, 2, s5
	s_cmp_gt_u32 s5, 2
	s_cselect_b32 s99, s50, s99
.Lscan_pfc_have:
	v_mov_b64_e32 v[112:113], v[128:129]
	v_mov_b64_e32 v[114:115], v[130:131]
	v_mov_b64_e32 v[116:117], v[132:133]
	v_mov_b64_e32 v[118:119], v[134:135]
	v_mov_b64_e32 v[120:121], v[100:101]
	v_mov_b64_e32 v[122:123], v[102:103]
	v_mov_b64_e32 v[124:125], v[104:105]
	v_mov_b64_e32 v[126:127], v[106:107]
	s_lshl_b32 s97, s99, 16
	s_lshl_b32 s98, s99, 12
	v_add_u32_e32 v68, s97, v245
	v_add_u32_e32 v69, 0x1000, v68
	s_cmp_lt_i32 s99, 4
	s_cbranch_scc1 .Lscan_pf_noq
	s_bitcmp1_b32 s8, 0
	s_cbranch_scc1 .Lscan_qk_rev0
	global_load_dword v100, v68, s[14:15]
	global_load_dword v128, v68, s[22:23]
	global_load_dword v101, v68, s[14:15] offset:1024
	global_load_dword v129, v68, s[22:23] offset:1024
	global_load_dword v102, v68, s[14:15] offset:2048
	global_load_dword v130, v68, s[22:23] offset:2048
	global_load_dword v103, v68, s[14:15] offset:3072
	global_load_dword v131, v68, s[22:23] offset:3072
	global_load_dword v104, v69, s[14:15]
	global_load_dword v132, v69, s[22:23]
	global_load_dword v105, v69, s[14:15] offset:1024
	global_load_dword v133, v69, s[22:23] offset:1024
	global_load_dword v106, v69, s[14:15] offset:2048
	global_load_dword v134, v69, s[22:23] offset:2048
	global_load_dword v107, v69, s[14:15] offset:3072
	global_load_dword v135, v69, s[22:23] offset:3072
	s_branch .Lscan_qk_done0
.Lscan_qk_rev0:
	global_load_dword v100, v69, s[14:15] offset:3072
	global_load_dword v128, v69, s[22:23] offset:3072
	global_load_dword v101, v69, s[14:15] offset:2048
	global_load_dword v129, v69, s[22:23] offset:2048
	global_load_dword v102, v69, s[14:15] offset:1024
	global_load_dword v130, v69, s[22:23] offset:1024
	global_load_dword v103, v69, s[14:15]
	global_load_dword v131, v69, s[22:23]
	global_load_dword v104, v68, s[14:15] offset:3072
	global_load_dword v132, v68, s[22:23] offset:3072
	global_load_dword v105, v68, s[14:15] offset:2048
	global_load_dword v133, v68, s[22:23] offset:2048
	global_load_dword v106, v68, s[14:15] offset:1024
	global_load_dword v134, v68, s[22:23] offset:1024
	global_load_dword v107, v68, s[14:15]
	global_load_dword v135, v68, s[22:23]

.Lscan_pf_noq:
	s_bitcmp1_b32 s8, 0
	s_cbranch_scc1 .Lscan_qk_rev1
	global_load_dword v100, v68, s[14:15]
	global_load_dword v101, v68, s[14:15] offset:1024
	global_load_dword v102, v68, s[14:15] offset:2048
	global_load_dword v103, v68, s[14:15] offset:3072
	global_load_dword v104, v69, s[14:15]
	global_load_dword v105, v69, s[14:15] offset:1024
	global_load_dword v106, v69, s[14:15] offset:2048
	global_load_dword v107, v69, s[14:15] offset:3072
	s_branch .Lscan_qk_done1
.Lscan_qk_rev1:
	global_load_dword v100, v69, s[14:15] offset:3072
	global_load_dword v101, v69, s[14:15] offset:2048
	global_load_dword v102, v69, s[14:15] offset:1024
	global_load_dword v103, v69, s[14:15]
	global_load_dword v104, v68, s[14:15] offset:3072
	global_load_dword v105, v68, s[14:15] offset:2048
	global_load_dword v106, v68, s[14:15] offset:1024
	global_load_dword v107, v68, s[14:15]

.Lscan_pf_v:
	v_add_u32_e32 v70, s98, v251
	v_mov_b32_e32 v71, 0
	v_lshl_add_u64 v[70:71], v[152:153], 0, v[70:71]
	global_load_dwordx4 v[96:99], v[70:71], off
	s_branch .Lscan_pfc_done
.Lscan_pfc_none:
	v_mov_b64_e32 v[112:113], v[128:129]
	v_mov_b64_e32 v[114:115], v[130:131]
	v_mov_b64_e32 v[116:117], v[132:133]
	v_mov_b64_e32 v[118:119], v[134:135]
	v_mov_b64_e32 v[120:121], v[100:101]
	v_mov_b64_e32 v[122:123], v[102:103]
	v_mov_b64_e32 v[124:125], v[104:105]
	v_mov_b64_e32 v[126:127], v[106:107]

; __device__ __forceinline__ int v_st(int k, int c) { const int kk = (k & ~0xC) | ((k & 4) << 1) | ((k & 8) >> 1); return ((kk >> 3) * 4 + (c >> 5)) * 512 + ((kk & 7) * 32 + (c & 31)) * 2; }
; __device__ __forceinline__ float bf2f(short s) { return __uint_as_float(((unsigned)(unsigned short)s) << 16); }
; __device__ __forceinline__ float bf2f(u16 u) { return __uint_as_float((unsigned)u << 16); }
; __device__ __forceinline__ u16 f2bf(float f) { return (u16)(pk2(f, 0.f) & 0xffffu); }
; __device__ __forceinline__ void scan_unit(const int unit, const Args& a, unsigned char* lds, const int mk_wid) {
;     ...
;           u16* qcol = qe + (g * 16) * QP + c; u16* kcol = ke + (g * 16) * QP + c; unsigned char* kdb = lds + L_KD + v_st(g * 16, c);
; #pragma unroll
;           for (int ii = 0; ii < 16; ++ii) { const float bb = bl[ii] + off;
;               const float qf = bf2f(qcol[ii * QP]), kf = bf2f(kcol[ii * QP]);
;               const float e = __builtin_amdgcn_exp2f(bb * 1.4426950408889634f), ker = kf * __builtin_amdgcn_rcpf(e);
;               qcol[ii * QP] = f2bf(qf * (0.088388347648318440f * e));
;               kcol[ii * QP] = f2bf(ker);
;               *(u16*)(kdb + v_st(ii, 0)) = f2bf(ker * dlc); } }
;         if (step + 1 < 36) GLA_LOAD(step + 1);
.Lscan_c2_nodl:
	v_mov_b32_e32 v71, 0xffff0000
	v_lshlrev_b32_e32 v218, 16, v112
	v_and_b32_e32 v219, v71, v112
	v_lshlrev_b32_e32 v220, 16, v120
	v_and_b32_e32 v221, v71, v120
	v_pk_mul_f32 v[218:219], v[170:171], v[218:219]
	v_pk_mul_f32 v[220:221], v[186:187], v[220:221]
	v_cvt_pk_bf16_f32 v224, v218, v219
	v_pk_mul_f32 v[222:223], v[92:93], v[220:221]
	v_cvt_pk_bf16_f32 v225, v220, v221
	ds_write_b32 v254, v224
	ds_write_b32 v254, v225 offset:17408
	v_cvt_pk_bf16_f32 v226, v222, v223
	ds_write_b32 v255, v226 offset:34816
	v_lshlrev_b32_e32 v228, 16, v113
	v_and_b32_e32 v229, v71, v113
	v_lshlrev_b32_e32 v230, 16, v121
	v_and_b32_e32 v231, v71, v121
	v_pk_mul_f32 v[228:229], v[172:173], v[228:229]
	v_pk_mul_f32 v[230:231], v[188:189], v[230:231]
	v_cvt_pk_bf16_f32 v234, v228, v229
	v_pk_mul_f32 v[232:233], v[92:93], v[230:231]
	v_cvt_pk_bf16_f32 v235, v230, v231
	ds_write_b32 v254, v234 offset:272
	ds_write_b32 v254, v235 offset:17680
	v_cvt_pk_bf16_f32 v236, v232, v233
	ds_write_b32 v255, v236 offset:34880
	v_lshlrev_b32_e32 v218, 16, v114
	v_and_b32_e32 v219, v71, v114
	v_lshlrev_b32_e32 v220, 16, v122
	v_and_b32_e32 v221, v71, v122
	v_pk_mul_f32 v[218:219], v[174:175], v[218:219]
	v_pk_mul_f32 v[220:221], v[190:191], v[220:221]
	v_cvt_pk_bf16_f32 v224, v218, v219
	v_pk_mul_f32 v[222:223], v[92:93], v[220:221]
	v_cvt_pk_bf16_f32 v225, v220, v221
	ds_write_b32 v254, v224 offset:544
	ds_write_b32 v254, v225 offset:17952
	v_cvt_pk_bf16_f32 v226, v222, v223
	ds_write_b32 v255, v226 offset:34944
	v_lshlrev_b32_e32 v228, 16, v115
	v_and_b32_e32 v229, v71, v115
	v_lshlrev_b32_e32 v230, 16, v123
	v_and_b32_e32 v231, v71, v123
	v_pk_mul_f32 v[228:229], v[176:177], v[228:229]
	v_pk_mul_f32 v[230:231], v[192:193], v[230:231]
	v_cvt_pk_bf16_f32 v234, v228, v229
	v_pk_mul_f32 v[232:233], v[92:93], v[230:231]
	v_cvt_pk_bf16_f32 v235, v230, v231
	ds_write_b32 v254, v234 offset:816
	ds_write_b32 v254, v235 offset:18224
	v_cvt_pk_bf16_f32 v236, v232, v233
	ds_write_b32 v255, v236 offset:35008
	v_lshlrev_b32_e32 v218, 16, v116
	v_and_b32_e32 v219, v71, v116
	v_lshlrev_b32_e32 v220, 16, v124
	v_and_b32_e32 v221, v71, v124
	v_pk_mul_f32 v[218:219], v[178:179], v[218:219]
	v_pk_mul_f32 v[220:221], v[194:195], v[220:221]
	v_cvt_pk_bf16_f32 v224, v218, v219
	v_pk_mul_f32 v[222:223], v[92:93], v[220:221]
	v_cvt_pk_bf16_f32 v225, v220, v221
	ds_write_b32 v254, v224 offset:1088
	ds_write_b32 v254, v225 offset:18496
	v_cvt_pk_bf16_f32 v226, v222, v223
	ds_write_b32 v255, v226 offset:36864
	v_lshlrev_b32_e32 v228, 16, v117
	v_and_b32_e32 v229, v71, v117
	v_lshlrev_b32_e32 v230, 16, v125
	v_and_b32_e32 v231, v71, v125
	v_pk_mul_f32 v[228:229], v[180:181], v[228:229]
	v_pk_mul_f32 v[230:231], v[196:197], v[230:231]
	v_cvt_pk_bf16_f32 v234, v228, v229
	v_pk_mul_f32 v[232:233], v[92:93], v[230:231]
	v_cvt_pk_bf16_f32 v235, v230, v231
	ds_write_b32 v254, v234 offset:1360
	ds_write_b32 v254, v235 offset:18768
	v_cvt_pk_bf16_f32 v236, v232, v233
	ds_write_b32 v255, v236 offset:36928
	v_lshlrev_b32_e32 v218, 16, v118
	v_and_b32_e32 v219, v71, v118
	v_lshlrev_b32_e32 v220, 16, v126
	v_and_b32_e32 v221, v71, v126
	v_pk_mul_f32 v[218:219], v[182:183], v[218:219]
	v_pk_mul_f32 v[220:221], v[198:199], v[220:221]
	v_cvt_pk_bf16_f32 v224, v218, v219
	v_pk_mul_f32 v[222:223], v[92:93], v[220:221]
	v_cvt_pk_bf16_f32 v225, v220, v221
	ds_write_b32 v254, v224 offset:1632
	ds_write_b32 v254, v225 offset:19040
	v_cvt_pk_bf16_f32 v226, v222, v223
	ds_write_b32 v255, v226 offset:36992
	v_lshlrev_b32_e32 v228, 16, v119
	v_and_b32_e32 v229, v71, v119
	v_lshlrev_b32_e32 v230, 16, v127
	v_and_b32_e32 v231, v71, v127
	v_pk_mul_f32 v[228:229], v[184:185], v[228:229]
	v_pk_mul_f32 v[230:231], v[200:201], v[230:231]
	v_cvt_pk_bf16_f32 v234, v228, v229
	v_pk_mul_f32 v[232:233], v[92:93], v[230:231]
	v_cvt_pk_bf16_f32 v235, v230, v231
	ds_write_b32 v254, v234 offset:1904
	ds_write_b32 v254, v235 offset:19312
	v_cvt_pk_bf16_f32 v236, v232, v233
	ds_write_b32 v255, v236 offset:37056
	s_add_i32 s58, s5, 1
	s_cmp_lt_i32 s34, 0
	s_cbranch_scc1 .Lscan_vw_ns
	s_cmp_lt_i32 s99, 0
	s_cbranch_scc1 .Lscan_vw_st0
	s_cmp_lt_i32 s99, 4
	s_cbranch_scc1 .Lscan_vw_st9
	s_waitcnt vmcnt(21)
	s_branch .Lscan_vwd
.Lscan_vw_st9:
	s_waitcnt vmcnt(13)
	s_branch .Lscan_vwd
.Lscan_vw_st0:
	s_waitcnt vmcnt(4)
	s_branch .Lscan_vwd
.Lscan_vw_ns:
	s_cmp_lt_i32 s99, 0
	s_cbranch_scc1 .Lscan_vw_ns0
	s_cmp_lt_i32 s99, 4
	s_cbranch_scc1 .Lscan_vw_ns9
	s_waitcnt vmcnt(17)
	s_branch .Lscan_vwd
.Lscan_vw_ns9:
	s_waitcnt vmcnt(9)
	s_branch .Lscan_vwd
.Lscan_vw_ns0:
	s_waitcnt vmcnt(0)
	s_branch .Lscan_vwd
